# attention: last two PV MFMAs of the first tile issued behind the barrier to cover the scalar DMA-issue block
# speedup vs baseline: 1.0028x; 1.0028x over previous
; #define SBAR() __builtin_amdgcn_sched_barrier(0)
; #define WBAR() do { asm volatile("s_waitcnt vmcnt(0) lgkmcnt(0)" ::: "memory"); __builtin_amdgcn_s_barrier(); asm volatile("" ::: "memory"); } while (0)
; __device__ __forceinline__ void attn_unit(const unsigned char* __restrict__ Qb, const unsigned char* __restrict__ Kh, const unsigned char* __restrict__ VTh, f16* __restrict__ Ob, int seq, LAS char* lds) {
;     ...
;         SBAR(); qkt(pB0, pB1, KSL(j), ka0, ka1, qf, negm);
;         finishSM(pA0, pA1, pa); SBAR();
;         pv_d0(o, VSL(j - 1), va0, va1, pa); partialSM<false>(pB0, pB1, negm, dlB, alB);
;         WBAR();
.LBB0_589:
	s_bitcmp1_b32 s15, 0
	s_cselect_b32 s0, 0x6000, 0
	s_add_i32 s0, s0, 0
	v_add_u32_e32 v0, s0, v244
	v_add_u32_e32 v210, s0, v245
	v_add_u32_e32 v211, 0xf000, v0
	v_add_u32_e32 v212, 0xf000, v210
	ds_read_b128 v[2:5], v0 offset:61504
	ds_read_b128 v[6:9], v210 offset:61504
	v_exp_f32_e32 v14, v116
	v_exp_f32_e32 v15, v117
	v_exp_f32_e32 v12, v114
	v_exp_f32_e32 v13, v115
	s_waitcnt lgkmcnt(4)
	v_mfma_scale_f32_32x32x64_f8f6f4 v[144:159], v[202:209], v[184:191], v[96:111], v234, v233 op_sel_hi:[0,0,0]
	ds_read_b128 v[202:205], v211 offset:6208
	ds_read_b128 v[206:209], v212 offset:6208
	v_exp_f32_e32 v114, v118
	v_exp_f32_e32 v115, v119
	v_exp_f32_e32 v119, v120
	v_exp_f32_e32 v120, v121
	v_cvt_pk_fp8_f32 v117, v14, v15
	v_exp_f32_e32 v10, v112
	v_exp_f32_e32 v11, v113
	s_waitcnt lgkmcnt(4)
	v_mfma_scale_f32_32x32x64_f8f6f4 v[128:143], v[194:201], v[184:191], v[96:111], v234, v233 op_sel_hi:[0,0,0]
	ds_read_b128 v[194:197], v0 offset:61568
	ds_read_b128 v[198:201], v210 offset:61568
	v_exp_f32_e32 v121, v122
	v_exp_f32_e32 v122, v123
	v_exp_f32_e32 v123, v124
	v_exp_f32_e32 v124, v125
	v_cvt_pk_fp8_f32 v117, v114, v115 op_sel:[0,0,1]
	v_cvt_pk_fp8_f32 v118, v119, v120
	v_exp_f32_e32 v125, v126
	s_waitcnt lgkmcnt(4)
	v_mfma_scale_f32_32x32x64_f8f6f4 v[144:159], v[2:9], v[176:183], v[144:159], v234, v233 op_sel_hi:[0,0,0]
	ds_read_b128 v[2:5], v211 offset:6272
	ds_read_b128 v[6:9], v212 offset:6272
	v_exp_f32_e32 v126, v127
	v_cvt_pk_fp8_f32 v112, v228, v229
	v_cvt_pk_fp8_f32 v116, v10, v11
	v_cvt_pk_fp8_f32 v113, v226, v227
	v_cvt_pk_fp8_f32 v114, v222, v223
	v_cvt_pk_fp8_f32 v115, v166, v167
	s_waitcnt lgkmcnt(4)
	v_mfma_scale_f32_32x32x64_f8f6f4 v[128:143], v[202:209], v[176:183], v[128:143], v234, v233 op_sel_hi:[0,0,0]
	v_cvt_pk_fp8_f32 v119, v123, v124
	v_cvt_pk_fp8_f32 v112, v220, v221 op_sel:[0,0,1]
	v_cvt_pk_fp8_f32 v116, v12, v13 op_sel:[0,0,1]
	v_cvt_pk_fp8_f32 v113, v224, v225 op_sel:[0,0,1]
	v_cvt_pk_fp8_f32 v114, v162, v163 op_sel:[0,0,1]
	v_cvt_pk_fp8_f32 v118, v121, v122 op_sel:[0,0,1]
	s_waitcnt lgkmcnt(2)
	v_mfma_scale_f32_32x32x64_f8f6f4 v[144:159], v[194:201], v[168:175], v[144:159], v234, v233 op_sel_hi:[0,0,0]
	v_cvt_pk_fp8_f32 v115, v164, v165 op_sel:[0,0,1]
	v_cvt_pk_fp8_f32 v119, v125, v126 op_sel:[0,0,1]
	v_mov_b32_e32 v161, v160
	v_mov_b32_e32 v162, v160
	v_mov_b32_e32 v163, v160
	s_waitcnt lgkmcnt(0)
	v_mfma_scale_f32_32x32x64_f8f6f4 v[128:143], v[2:9], v[168:175], v[128:143], v234, v233 op_sel_hi:[0,0,0]
	v_mov_b32_e32 v164, v160
	v_mov_b32_e32 v165, v160
	v_mov_b32_e32 v166, v160
	v_mov_b32_e32 v167, v160
	s_add_i32 s66, s21, -2
	s_ashr_i32 s38, s66, 1
	s_mul_hi_i32 s0, s38, 0x55555556
	s_lshr_b32 s1, s0, 31
	s_add_i32 s0, s0, s1
	s_mul_i32 s0, s0, 3
	s_sub_i32 s0, s38, s0
	s_lshl_b32 s0, s0, 14
	s_add_i32 s0, s0, 0
	v_add_u32_e32 v0, s0, v241
	v_add_u32_e32 v11, s0, v240
	ds_read_b128 v[208:211], v0
	ds_read_b128 v[212:215], v11
	ds_read_b128 v[200:203], v0 offset:2048
	ds_read_b128 v[204:207], v11 offset:2048
	ds_read_b128 v[192:195], v0 offset:4096
	ds_read_b128 v[196:199], v11 offset:4096
	ds_read_b128 v[2:5], v0 offset:6144
	ds_read_b128 v[6:9], v11 offset:6144
	v_mov_b32_e32 v125, 0x19000
	v_lshl_add_u32 v126, v216, 4, v125
	v_lshl_add_u32 v127, v216, 2, v125
	ds_read_b128 v[120:123], v126
	ds_read_b32 v124, v127 offset:8192
	v_max_f32_e32 v0, v145, v145
	v_max_f32_e32 v125, v144, v144
	v_max_f32_e32 v0, v125, v0
	v_max3_f32 v0, v0, v146, v147
	v_max3_f32 v0, v0, v148, v149
	v_max3_f32 v0, v0, v150, v151
	v_max3_f32 v0, v0, v152, v153
	v_max3_f32 v0, v0, v154, v155
	v_max3_f32 v0, v0, v156, v157
	v_max3_f32 v0, v0, v158, v159
	s_waitcnt lgkmcnt(8)
	v_mfma_scale_f32_32x32x64_f8f6f4 v[64:79], v[112:119], v[208:215], v[64:79], v234, v234 op_sel_hi:[0,0,0]
	v_exp_f32_e32 v14, v144
	v_exp_f32_e32 v15, v145
	v_exp_f32_e32 v10, v148
	v_exp_f32_e32 v11, v149
	v_max3_f32 v0, v0, v128, v129
	v_max3_f32 v0, v0, v130, v131
	v_max3_f32 v0, v0, v132, v133
	v_max3_f32 v0, v0, v134, v135
	s_waitcnt lgkmcnt(6)
	v_mfma_scale_f32_32x32x64_f8f6f4 v[48:63], v[112:119], v[200:207], v[48:63], v234, v234 op_sel_hi:[0,0,0]
	v_exp_f32_e32 v12, v150
	v_exp_f32_e32 v13, v151
	v_max3_f32 v0, v0, v136, v137
	v_max3_f32 v0, v0, v138, v139
	v_max3_f32 v0, v0, v140, v141
	v_max3_f32 v0, v0, v142, v143
	s_waitcnt lgkmcnt(4)
	v_mfma_scale_f32_32x32x64_f8f6f4 v[32:47], v[112:119], v[192:199], v[32:47], v234, v234 op_sel_hi:[0,0,0]
	v_exp_f32_e32 v192, v146
	v_exp_f32_e32 v193, v147
	v_mov_b32_e32 v125, v0
	s_nop 1
	v_permlane32_swap_b32_e32 v0, v125
	v_max_f32_e32 v125, v125, v125
	v_max_f32_e32 v0, v0, v0
	s_waitcnt vmcnt(0) lgkmcnt(0)
	s_barrier
; #define LAS __attribute__((address_space(3)))
; #define MFMA8(A, B, C) __builtin_amdgcn_mfma_scale_f32_32x32x64_f8f6f4(A, B, C, 0, 0, 0, 0x7F7F7F7F, 0, 0x7F7F7F7F)
; __device__ __forceinline__ v8i ld32(const LAS char* a0, const LAS char* a1) { const v4i x = *(const LAS v4i*)a0, y = *(const LAS v4i*)a1; return (v8i){x[0], x[1], x[2], x[3], y[0], y[1], y[2], y[3]}; }
; #define WBAR() do { asm volatile("s_waitcnt vmcnt(0) lgkmcnt(0)" ::: "memory"); __builtin_amdgcn_s_barrier(); asm volatile("" ::: "memory"); } while (0)
; #define FIX(a, dlt, P0, P1) do { if (__any((dlt) > 0.f)) { if (hi == 0) al_l[r32] = (a); asm volatile("s_waitcnt lgkmcnt(0)" ::: "memory"); \
;     _Pragma("unroll") for (int d = 0; d < 5; ++d) _Pragma("unroll") for (int r = 0; r < 16; ++r) o[d][r] *= al_l[crow(r, hi)]; \
;     _Pragma("unroll") for (int r = 0; r < 16; ++r) { P0[r] *= (a); P1[r] -= (dlt); negm[r] -= (dlt); } } } while (0)
; __device__ __forceinline__ void pv_d0(f32x16* o, const LAS char* Vs, int va0, int va1, v8i pa) {
; #pragma unroll
;     for (int d0 = 0; d0 < 4; ++d0) { const v8i vf = ld32(Vs + va0 + 2048 * d0, Vs + va1 + 2048 * d0); o[d0] = MFMA8(pa, vf, o[d0]); }
;     const v8i ones = {0x38383838, 0x38383838, 0x38383838, 0x38383838, 0x38383838, 0x38383838, 0x38383838, 0x38383838};
;     o[4] = MFMA8(pa, ones, o[4]);
; __device__ __forceinline__ void attn_unit(const unsigned char* __restrict__ Qb, const unsigned char* __restrict__ Kh, const unsigned char* __restrict__ VTh, f16* __restrict__ Ob, int seq, LAS char* lds) {
;     ...
;         WBAR();
;         { const int J = (j - 1) >> 1; if (J + 2 < NS) ISSUE(J + 2); }
;         FIX(alB, dlB, pB0, pB1);
	v_max_f32_e32 v0, v0, v125
	s_add_i32 s42, s38, 2
	v_cmp_ge_f32_e64 s[0:1], s67, v0
	s_cmp_ge_i32 s42, s14
	s_cbranch_scc1 .Lattn_noissue
	s_bitcmp1_b32 s21, 1
	s_cselect_b32 s44, 0x6000, 0
	v_add_u32_e32 v126, s44, v244
	v_add_u32_e32 v127, s44, v245
	ds_read_b128 v[208:211], v126 offset:49152
	ds_read_b128 v[212:215], v127 offset:49152
	v_mfma_scale_f32_32x32x64_f8f6f4 v[16:31], v[112:119], v[2:9], v[16:31], v234, v234 op_sel_hi:[0,0,0]
	s_ashr_i32 s43, s42, 31
	s_mul_i32 s38, s42, 0x18000
	s_mul_hi_i32 s39, s42, 0x18000
	s_add_u32 s38, s24, s38
	s_addc_u32 s39, s25, s39
	s_lshl_b64 s[40:41], s[42:43], 14
	s_add_u32 s40, s52, s40
	s_addc_u32 s41, s53, s41
	s_mul_hi_i32 s43, s42, 0x55555556
	s_lshr_b32 s67, s43, 31
	s_add_i32 s43, s43, s67
	s_mul_i32 s43, s43, 3
	s_sub_i32 s42, s42, s43
	s_lshl_b32 s67, s42, 14
	s_bitcmp1_b32 s66, 1
	s_mov_b32 s42, 0xa000
	s_cselect_b32 s66, 0x10000, s42
	s_add_i32 s42, s67, s28
	s_add_i32 s43, s29, s66
	s_and_b64 vcc, s[54:55], exec
	s_cselect_b32 s42, s42, s43
	s_mov_b32 m0, s42
	s_and_b64 vcc, exec, s[56:57]
	s_cselect_b32 s44, s38, s40
	s_cselect_b32 s45, s39, s41
	global_load_lds_dwordx4 v120, s[44:45]
	s_add_i32 s42, s67, s35
	s_add_i32 s43, s2, s66
	s_and_b64 vcc, s[58:59], exec
	s_cselect_b32 s42, s42, s43
	s_mov_b32 m0, s42
	s_and_b64 vcc, exec, s[4:5]
	s_cselect_b32 s44, s40, s38
	s_cselect_b32 s45, s41, s39
	global_load_lds_dwordx4 v121, s[44:45]
	v_exp_f32_e32 v6, v152
	v_exp_f32_e32 v7, v153
	v_exp_f32_e32 v8, v154
	v_exp_f32_e32 v9, v155
	v_exp_f32_e32 v2, v156
	v_exp_f32_e32 v3, v157
	v_exp_f32_e32 v4, v158
	v_exp_f32_e32 v5, v159
	v_mfma_scale_f32_32x32x64_f8f6f4 v[80:95], v[112:119], v[160:167], v[80:95], v234, v234 op_sel_hi:[0,0,0]
	s_add_i32 s42, s67, s26
	s_add_i32 s43, s27, s66
	s_and_b64 vcc, s[60:61], exec
	s_cselect_b32 s42, s42, s43
	s_mov_b32 m0, s42
	s_and_b64 vcc, exec, s[6:7]
	s_cselect_b32 s44, s40, s38
	s_cselect_b32 s45, s41, s39
	global_load_lds_dwordx4 v122, s[44:45]
	s_add_i32 s42, s67, s31
	s_add_i32 s43, s49, s66
	s_and_b64 vcc, s[62:63], exec
	s_cselect_b32 s42, s42, s43
	s_mov_b32 m0, s42
	s_and_b64 vcc, exec, s[8:9]
	s_cselect_b32 s44, s40, s38
	s_cselect_b32 s45, s41, s39
	global_load_lds_dwordx4 v123, s[44:45]
	s_add_i32 s42, s67, s18
	s_add_i32 s43, s33, s66
	s_and_b64 vcc, s[64:65], exec
	s_cselect_b32 s42, s42, s43
	s_mov_b32 m0, s42
	s_and_b64 vcc, exec, s[10:11]
	s_cselect_b32 s44, s40, s38
	s_cselect_b32 s45, s41, s39
	global_load_lds_dwordx4 v124, s[44:45]
	s_mov_b32 s67, 0x41000000
	ds_read_b128 v[120:123], v126 offset:55296
	ds_read_b128 v[124:127], v127 offset:55296
	v_add_f32_e32 v0, -4.0, v0
	s_cmp_lg_u64 s[0:1], exec
	v_max_f32_e32 v0, 0, v0
	s_cselect_b64 vcc, -1, 0
	v_cndmask_b32_e32 v0, 0, v0, vcc
	v_cmp_lt_f32_e32 vcc, 0, v0
	s_cbranch_vccz .LBB0_615
	s_branch .Lattn_fix1
.Lattn_noissue:
	s_bitcmp1_b32 s21, 1
	s_cselect_b32 s44, 0x6000, 0
	v_add_u32_e32 v126, s44, v244
	v_add_u32_e32 v127, s44, v245
	ds_read_b128 v[208:211], v126 offset:49152
	ds_read_b128 v[212:215], v127 offset:49152
	v_mfma_scale_f32_32x32x64_f8f6f4 v[16:31], v[112:119], v[2:9], v[16:31], v234, v234 op_sel_hi:[0,0,0]
	v_exp_f32_e32 v6, v152
	v_exp_f32_e32 v7, v153
	v_exp_f32_e32 v8, v154
	v_exp_f32_e32 v9, v155
	v_exp_f32_e32 v2, v156
	v_exp_f32_e32 v3, v157
	v_exp_f32_e32 v4, v158
	v_exp_f32_e32 v5, v159
	v_mfma_scale_f32_32x32x64_f8f6f4 v[80:95], v[112:119], v[160:167], v[80:95], v234, v234 op_sel_hi:[0,0,0]
	ds_read_b128 v[120:123], v126 offset:55296
	ds_read_b128 v[124:127], v127 offset:55296
	v_add_f32_e32 v0, -4.0, v0
	s_cmp_lg_u64 s[0:1], exec
	v_max_f32_e32 v0, 0, v0
	s_cselect_b64 vcc, -1, 0
	v_cndmask_b32_e32 v0, 0, v0, vcc
	v_cmp_lt_f32_e32 vcc, 0, v0
	s_cbranch_vccz .LBB0_615
